# v99 + P8a: sample items spread over all 8 XCDs (blocks with (bid>>3)<16 take item 16*(bid&7)+(bid>>3)) instead of XCDs 0..3 only
# baseline (speedup 1.0000x reference)
.LBB0_1645:
	s_or_b64 exec, exec, s[8:9]
	s_add_i32 s0, s18, 3
	s_ashr_i32 s1, s0, 31
	v_lshl_add_u64 v[4:5], v[4:5], 1, s[12:13]
	s_lshl_b64 s[0:1], s[0:1], 12
	s_add_i32 s2, s2, s92
	s_add_i32 s18, s18, s24
	v_cvt_pk_bf16_f32 v0, v0, v1
	v_cvt_pk_bf16_f32 v1, v2, v3
	v_lshl_add_u64 v[2:3], v[4:5], 0, s[0:1]
	s_cmpk_eq_u32 s92, 0x100
	s_cbranch_scc0 .Lp8a_xs_done
	s_sub_i32 s98, s2, 0x800
	s_cmpk_lt_u32 s98, 0x100
	s_cbranch_scc0 .Lp8a_xs_done
	s_and_b32 s99, s98, 31
	s_cmpk_lt_u32 s99, 16
	s_cbranch_scc1 .Lp8a_xs_take
	s_movk_i32 s2, 0x1000
	s_branch .Lp8a_xs_done
.Lp8a_xs_take:
	s_lshr_b32 s98, s98, 5
	s_lshl_b32 s98, s98, 4
	s_add_i32 s98, s98, s99
	s_add_i32 s2, s98, 0x800
	s_lshl_b32 s18, s2, 2
